# prologue de-serialisation: GLA-prep gate weight staging issues its seven strided dword loads per thread together behind one wait (branch-free address select) instead of a load-wait-write loop
# speedup vs baseline: 1.0022x; 1.0022x over previous
.LBB0_568:
	v_add_u32_e32 v2, 0x100, v2
	v_cmp_lt_u32_e32 vcc, s1, v2
	ds_write_b16 v0, v1
	s_or_b64 s[2:3], vcc, s[2:3]
	v_add_u32_e32 v0, 0x200, v0
	s_andn2_b64 exec, exec, s[2:3]
	s_cbranch_execnz .LBB0_568
	s_or_b64 exec, exec, s[2:3]
	s_lshl_b32 s1, s0, 1
	s_and_b32 s2, s0, -16
	s_and_b32 s1, s1, 14
	s_bfe_u32 s3, s0, 0x10003
	s_or_b32 s1, s1, s2
	s_or_b32 s1, s1, s3
	s_load_dwordx4 s[40:43], s[54:55], 0x88
	v_lshl_add_u32 v5, s1, 1, v122
	v_and_b32_e32 v97, 3, v5
	v_mul_u32_u24_e32 v4, 48, v97
	v_lshlrev_b32_e32 v0, 2, v4
	v_lshlrev_b32_e32 v78, 2, v123
	v_readlane_b32 s2, v254, 57
	s_lshl_b32 s10, s44, 1
	v_or_b32_e32 v10, 0xfffffd00, v4
	s_waitcnt lgkmcnt(0)
	v_lshl_add_u64 v[2:3], s[40:41], 0, v[0:1]
	v_add3_u32 v11, v93, v78, s2
	s_mov_b64 s[2:3], 0
	v_mov_b32_e32 v12, v123
	s_movk_i32 s14, 0x7f
	s_mov_b32 s15, 0xaaab
	v_mov_b32_e32 v245, 0
	v_mov_b32_e32 v249, 0
	v_mov_b32_e32 v241, v123
	v_cmp_lt_u32_e32 vcc, 0x32f, v241
	v_subrev_u32_e32 v242, 0x330, v241
	s_nop 1
	v_cndmask_b32_e32 v243, v241, v242, vcc
	v_cndmask_b32_e64 v253, 0, 1, vcc
	v_or_b32_e32 v253, s10, v253
	v_mul_lo_u32 v244, v253, s90
	v_mul_u32_u24_e32 v252, 0xaaab, v243
	v_add3_u32 v244, v10, v243, v244
	v_lshrrev_b32_e32 v252, 21, v252
	v_lshl_add_u64 v[246:247], v[244:245], 2, s[42:43]
	v_mul_u32_u24_e32 v242, 48, v252
	v_lshl_add_u32 v248, v253, 4, v252
	v_sub_u32_e32 v242, v243, v242
	v_mul_u32_u24_e32 v248, 0x300, v248
	v_cmp_lt_u32_e32 vcc, 0x2ff, v243
	v_lshl_add_u32 v248, v242, 2, v248
	v_lshl_add_u64 v[250:251], v[2:3], 0, v[248:249]
	s_nop 0
	v_cndmask_b32_e32 v250, v250, v246, vcc
	v_cndmask_b32_e32 v251, v251, v247, vcc
	global_load_dword v234, v[250:251], off
	v_add_u32_e32 v241, 0x100, v123
	v_cmp_lt_u32_e32 vcc, 0x32f, v241
	v_subrev_u32_e32 v242, 0x330, v241
	s_nop 1
	v_cndmask_b32_e32 v243, v241, v242, vcc
	v_cndmask_b32_e64 v253, 0, 1, vcc
	v_or_b32_e32 v253, s10, v253
	v_mul_lo_u32 v244, v253, s90
	v_mul_u32_u24_e32 v252, 0xaaab, v243
	v_add3_u32 v244, v10, v243, v244
	v_lshrrev_b32_e32 v252, 21, v252
	v_lshl_add_u64 v[246:247], v[244:245], 2, s[42:43]
	v_mul_u32_u24_e32 v242, 48, v252
	v_lshl_add_u32 v248, v253, 4, v252
	v_sub_u32_e32 v242, v243, v242
	v_mul_u32_u24_e32 v248, 0x300, v248
	v_cmp_lt_u32_e32 vcc, 0x2ff, v243
	v_lshl_add_u32 v248, v242, 2, v248
	v_lshl_add_u64 v[250:251], v[2:3], 0, v[248:249]
	s_nop 0
	v_cndmask_b32_e32 v250, v250, v246, vcc
	v_cndmask_b32_e32 v251, v251, v247, vcc
	global_load_dword v235, v[250:251], off
	v_add_u32_e32 v241, 0x200, v123
	v_cmp_lt_u32_e32 vcc, 0x32f, v241
	v_subrev_u32_e32 v242, 0x330, v241
	s_nop 1
	v_cndmask_b32_e32 v243, v241, v242, vcc
	v_cndmask_b32_e64 v253, 0, 1, vcc
	v_or_b32_e32 v253, s10, v253
	v_mul_lo_u32 v244, v253, s90
	v_mul_u32_u24_e32 v252, 0xaaab, v243
	v_add3_u32 v244, v10, v243, v244
	v_lshrrev_b32_e32 v252, 21, v252
	v_lshl_add_u64 v[246:247], v[244:245], 2, s[42:43]
	v_mul_u32_u24_e32 v242, 48, v252
	v_lshl_add_u32 v248, v253, 4, v252
	v_sub_u32_e32 v242, v243, v242
	v_mul_u32_u24_e32 v248, 0x300, v248
	v_cmp_lt_u32_e32 vcc, 0x2ff, v243
	v_lshl_add_u32 v248, v242, 2, v248
	v_lshl_add_u64 v[250:251], v[2:3], 0, v[248:249]
	s_nop 0
	v_cndmask_b32_e32 v250, v250, v246, vcc
	v_cndmask_b32_e32 v251, v251, v247, vcc
	global_load_dword v236, v[250:251], off
	v_add_u32_e32 v241, 0x300, v123
	v_cmp_lt_u32_e32 vcc, 0x32f, v241
	v_subrev_u32_e32 v242, 0x330, v241
	s_nop 1
	v_cndmask_b32_e32 v243, v241, v242, vcc
	v_cndmask_b32_e64 v253, 0, 1, vcc
	v_or_b32_e32 v253, s10, v253
	v_mul_lo_u32 v244, v253, s90
	v_mul_u32_u24_e32 v252, 0xaaab, v243
	v_add3_u32 v244, v10, v243, v244
	v_lshrrev_b32_e32 v252, 21, v252
	v_lshl_add_u64 v[246:247], v[244:245], 2, s[42:43]
	v_mul_u32_u24_e32 v242, 48, v252
	v_lshl_add_u32 v248, v253, 4, v252
	v_sub_u32_e32 v242, v243, v242
	v_mul_u32_u24_e32 v248, 0x300, v248
	v_cmp_lt_u32_e32 vcc, 0x2ff, v243
	v_lshl_add_u32 v248, v242, 2, v248
	v_lshl_add_u64 v[250:251], v[2:3], 0, v[248:249]
	s_nop 0
	v_cndmask_b32_e32 v250, v250, v246, vcc
	v_cndmask_b32_e32 v251, v251, v247, vcc
	global_load_dword v237, v[250:251], off
	v_add_u32_e32 v241, 0x400, v123
	v_cmp_lt_u32_e32 vcc, 0x32f, v241
	v_subrev_u32_e32 v242, 0x330, v241
	s_nop 1
	v_cndmask_b32_e32 v243, v241, v242, vcc
	v_cndmask_b32_e64 v253, 0, 1, vcc
	v_or_b32_e32 v253, s10, v253
	v_mul_lo_u32 v244, v253, s90
	v_mul_u32_u24_e32 v252, 0xaaab, v243
	v_add3_u32 v244, v10, v243, v244
	v_lshrrev_b32_e32 v252, 21, v252
	v_lshl_add_u64 v[246:247], v[244:245], 2, s[42:43]
	v_mul_u32_u24_e32 v242, 48, v252
	v_lshl_add_u32 v248, v253, 4, v252
	v_sub_u32_e32 v242, v243, v242
	v_mul_u32_u24_e32 v248, 0x300, v248
	v_cmp_lt_u32_e32 vcc, 0x2ff, v243
	v_lshl_add_u32 v248, v242, 2, v248
	v_lshl_add_u64 v[250:251], v[2:3], 0, v[248:249]
	s_nop 0
	v_cndmask_b32_e32 v250, v250, v246, vcc
	v_cndmask_b32_e32 v251, v251, v247, vcc
	global_load_dword v238, v[250:251], off
	v_add_u32_e32 v241, 0x500, v123
	v_cmp_lt_u32_e32 vcc, 0x32f, v241
	v_subrev_u32_e32 v242, 0x330, v241
	s_nop 1
	v_cndmask_b32_e32 v243, v241, v242, vcc
	v_cndmask_b32_e64 v253, 0, 1, vcc
	v_or_b32_e32 v253, s10, v253
	v_mul_lo_u32 v244, v253, s90
	v_mul_u32_u24_e32 v252, 0xaaab, v243
	v_add3_u32 v244, v10, v243, v244
	v_lshrrev_b32_e32 v252, 21, v252
	v_lshl_add_u64 v[246:247], v[244:245], 2, s[42:43]
	v_mul_u32_u24_e32 v242, 48, v252
	v_lshl_add_u32 v248, v253, 4, v252
	v_sub_u32_e32 v242, v243, v242
	v_mul_u32_u24_e32 v248, 0x300, v248
	v_cmp_lt_u32_e32 vcc, 0x2ff, v243
	v_lshl_add_u32 v248, v242, 2, v248
	v_lshl_add_u64 v[250:251], v[2:3], 0, v[248:249]
	s_nop 0
	v_cndmask_b32_e32 v250, v250, v246, vcc
	v_cndmask_b32_e32 v251, v251, v247, vcc
	global_load_dword v239, v[250:251], off
	v_cmp_gt_u32_e32 vcc, 96, v123
	s_nop 1
	s_and_saveexec_b64 s[8:9], vcc
	v_add_u32_e32 v241, 0x600, v123
	v_cmp_lt_u32_e32 vcc, 0x32f, v241
	v_subrev_u32_e32 v242, 0x330, v241
	s_nop 1
	v_cndmask_b32_e32 v243, v241, v242, vcc
	v_cndmask_b32_e64 v253, 0, 1, vcc
	v_or_b32_e32 v253, s10, v253
	v_mul_lo_u32 v244, v253, s90
	v_mul_u32_u24_e32 v252, 0xaaab, v243
	v_add3_u32 v244, v10, v243, v244
	v_lshrrev_b32_e32 v252, 21, v252
	v_lshl_add_u64 v[246:247], v[244:245], 2, s[42:43]
	v_mul_u32_u24_e32 v242, 48, v252
	v_lshl_add_u32 v248, v253, 4, v252
	v_sub_u32_e32 v242, v243, v242
	v_mul_u32_u24_e32 v248, 0x300, v248
	v_cmp_lt_u32_e32 vcc, 0x2ff, v243
	v_lshl_add_u32 v248, v242, 2, v248
	v_lshl_add_u64 v[250:251], v[2:3], 0, v[248:249]
	s_nop 0
	v_cndmask_b32_e32 v250, v250, v246, vcc
	v_cndmask_b32_e32 v251, v251, v247, vcc
	global_load_dword v240, v[250:251], off
	s_waitcnt vmcnt(0)
	ds_write_b32 v11, v240 offset:6144
	s_or_b64 exec, exec, s[8:9]
	ds_write_b32 v11, v234
	ds_write_b32 v11, v235 offset:1024
	ds_write_b32 v11, v236 offset:2048
	ds_write_b32 v11, v237 offset:3072
	ds_write_b32 v11, v238 offset:4096
	ds_write_b32 v11, v239 offset:5120
	s_mov_b64 s[2:3], 0
